# GEMM epilogue de-serialisation: S5 GLU epilogue loads 16 z values per batch with one wait (was load/wait per element, 96 waits per tile)
# speedup vs baseline: 1.0911x; 1.0125x over previous
.LBB0_502:
	s_andn2_b64 vcc, exec, s[2:3]
	s_cbranch_vccnz .LBB0_504
	v_lshlrev_b32_e32 v244, 11, v108
	v_lshl_add_u32 v244, v100, 1, v244
	v_or_b32_e32 v249, v108, v146
	v_lshlrev_b32_e32 v249, 11, v249
	v_and_b32_e32 v250, -2, v100
	v_lshl_add_u32 v249, v250, 1, v249
	v_mov_b32_e32 v245, v244
	v_mov_b32_e32 v236, v249
	v_add_u32_e32 v246, 0x1000, v244
	v_add_u32_e32 v237, 0x1000, v249
	v_add_u32_e32 v247, 0x4000, v244
	v_add_u32_e32 v238, 0x4000, v249
	v_add_u32_e32 v248, 0x5000, v244
	v_add_u32_e32 v239, 0x5000, v249
	global_load_ushort v204, v245, s[52:53]
	global_load_ushort v205, v245, s[52:53] offset:2048
	global_load_ushort v206, v245, s[52:53] offset:64
	global_load_ushort v207, v245, s[52:53] offset:2112
	global_load_ushort v208, v246, s[52:53]
	global_load_ushort v209, v246, s[52:53] offset:2048
	global_load_ushort v210, v246, s[52:53] offset:64
	global_load_ushort v211, v246, s[52:53] offset:2112
	global_load_ushort v212, v247, s[52:53]
	global_load_ushort v213, v247, s[52:53] offset:2048
	global_load_ushort v214, v247, s[52:53] offset:64
	global_load_ushort v215, v247, s[52:53] offset:2112
	global_load_ushort v216, v248, s[52:53]
	global_load_ushort v217, v248, s[52:53] offset:2048
	global_load_ushort v218, v248, s[52:53] offset:64
	global_load_ushort v219, v248, s[52:53] offset:2112
	v_mul_f32_e32 v82, 0xbfb8aa3b, v82
	v_mul_f32_e32 v83, 0xbfb8aa3b, v83
	v_mul_f32_e32 v66, 0xbfb8aa3b, v66
	v_mul_f32_e32 v67, 0xbfb8aa3b, v67
	v_exp_f32_e32 v82, v82
	v_exp_f32_e32 v83, v83
	v_exp_f32_e32 v66, v66
	v_exp_f32_e32 v67, v67
	v_add_f32_e32 v82, 1.0, v82
	v_add_f32_e32 v83, 1.0, v83
	v_add_f32_e32 v66, 1.0, v66
	v_add_f32_e32 v67, 1.0, v67
	v_rcp_f32_e32 v82, v82
	v_rcp_f32_e32 v83, v83
	v_rcp_f32_e32 v66, v66
	v_rcp_f32_e32 v67, v67
	v_mul_f32_e32 v84, 0xbfb8aa3b, v84
	v_mul_f32_e32 v85, 0xbfb8aa3b, v85
	v_mul_f32_e32 v68, 0xbfb8aa3b, v68
	v_mul_f32_e32 v69, 0xbfb8aa3b, v69
	v_exp_f32_e32 v84, v84
	v_exp_f32_e32 v85, v85
	v_exp_f32_e32 v68, v68
	v_exp_f32_e32 v69, v69
	v_add_f32_e32 v84, 1.0, v84
	v_add_f32_e32 v85, 1.0, v85
	v_add_f32_e32 v68, 1.0, v68
	v_add_f32_e32 v69, 1.0, v69
	v_rcp_f32_e32 v84, v84
	v_rcp_f32_e32 v85, v85
	v_rcp_f32_e32 v68, v68
	v_rcp_f32_e32 v69, v69
	v_mul_f32_e32 v86, 0xbfb8aa3b, v86
	v_mul_f32_e32 v87, 0xbfb8aa3b, v87
	v_mul_f32_e32 v70, 0xbfb8aa3b, v70
	v_mul_f32_e32 v71, 0xbfb8aa3b, v71
	v_exp_f32_e32 v86, v86
	v_exp_f32_e32 v87, v87
	v_exp_f32_e32 v70, v70
	v_exp_f32_e32 v71, v71
	v_add_f32_e32 v86, 1.0, v86
	v_add_f32_e32 v87, 1.0, v87
	v_add_f32_e32 v70, 1.0, v70
	v_add_f32_e32 v71, 1.0, v71
	v_rcp_f32_e32 v86, v86
	v_rcp_f32_e32 v87, v87
	v_rcp_f32_e32 v70, v70
	v_rcp_f32_e32 v71, v71
	v_mul_f32_e32 v88, 0xbfb8aa3b, v88
	v_mul_f32_e32 v89, 0xbfb8aa3b, v89
	v_mul_f32_e32 v72, 0xbfb8aa3b, v72
	v_mul_f32_e32 v73, 0xbfb8aa3b, v73
	v_exp_f32_e32 v88, v88
	v_exp_f32_e32 v89, v89
	v_exp_f32_e32 v72, v72
	v_exp_f32_e32 v73, v73
	v_add_f32_e32 v88, 1.0, v88
	v_add_f32_e32 v89, 1.0, v89
	v_add_f32_e32 v72, 1.0, v72
	v_add_f32_e32 v73, 1.0, v73
	v_rcp_f32_e32 v88, v88
	v_rcp_f32_e32 v89, v89
	v_rcp_f32_e32 v72, v72
	v_rcp_f32_e32 v73, v73
	s_waitcnt vmcnt(0)
	v_lshlrev_b32_e32 v204, 16, v204
	v_lshlrev_b32_e32 v205, 16, v205
	v_lshlrev_b32_e32 v206, 16, v206
	v_lshlrev_b32_e32 v207, 16, v207
	v_lshlrev_b32_e32 v208, 16, v208
	v_lshlrev_b32_e32 v209, 16, v209
	v_lshlrev_b32_e32 v210, 16, v210
	v_lshlrev_b32_e32 v211, 16, v211
	v_lshlrev_b32_e32 v212, 16, v212
	v_lshlrev_b32_e32 v213, 16, v213
	v_lshlrev_b32_e32 v214, 16, v214
	v_lshlrev_b32_e32 v215, 16, v215
	v_lshlrev_b32_e32 v216, 16, v216
	v_lshlrev_b32_e32 v217, 16, v217
	v_lshlrev_b32_e32 v218, 16, v218
	v_lshlrev_b32_e32 v219, 16, v219
	v_mul_f32_e32 v204, v82, v204
	v_mul_f32_e32 v205, v83, v205
	v_mul_f32_e32 v206, v66, v206
	v_mul_f32_e32 v207, v67, v207
	v_mul_f32_e32 v208, v84, v208
	v_mul_f32_e32 v209, v85, v209
	v_mul_f32_e32 v210, v68, v210
	v_mul_f32_e32 v211, v69, v211
	v_mul_f32_e32 v212, v86, v212
	v_mul_f32_e32 v213, v87, v213
	v_mul_f32_e32 v214, v70, v214
	v_mul_f32_e32 v215, v71, v215
	v_mul_f32_e32 v216, v88, v216
	v_mul_f32_e32 v217, v89, v217
	v_mul_f32_e32 v218, v72, v218
	v_mul_f32_e32 v219, v73, v219
	v_cndmask_b32_e64 v220, v204, v205, s[40:41]
	v_cndmask_b32_e64 v221, v206, v207, s[40:41]
	v_cndmask_b32_e64 v222, v208, v209, s[40:41]
	v_cndmask_b32_e64 v223, v210, v211, s[40:41]
	v_cndmask_b32_e64 v224, v212, v213, s[40:41]
	v_cndmask_b32_e64 v225, v214, v215, s[40:41]
	v_cndmask_b32_e64 v226, v216, v217, s[40:41]
	v_cndmask_b32_e64 v227, v218, v219, s[40:41]
	v_mov_b32_dpp v220, v220 quad_perm:[1,0,3,2] row_mask:0xf bank_mask:0xf bound_ctrl:1
	v_mov_b32_dpp v221, v221 quad_perm:[1,0,3,2] row_mask:0xf bank_mask:0xf bound_ctrl:1
	v_mov_b32_dpp v222, v222 quad_perm:[1,0,3,2] row_mask:0xf bank_mask:0xf bound_ctrl:1
	v_mov_b32_dpp v223, v223 quad_perm:[1,0,3,2] row_mask:0xf bank_mask:0xf bound_ctrl:1
	v_mov_b32_dpp v224, v224 quad_perm:[1,0,3,2] row_mask:0xf bank_mask:0xf bound_ctrl:1
	v_mov_b32_dpp v225, v225 quad_perm:[1,0,3,2] row_mask:0xf bank_mask:0xf bound_ctrl:1
	v_mov_b32_dpp v226, v226 quad_perm:[1,0,3,2] row_mask:0xf bank_mask:0xf bound_ctrl:1
	v_mov_b32_dpp v227, v227 quad_perm:[1,0,3,2] row_mask:0xf bank_mask:0xf bound_ctrl:1
	v_cndmask_b32_e64 v204, v220, v204, s[40:41]
	v_cndmask_b32_e64 v205, v205, v220, s[40:41]
	v_cndmask_b32_e64 v206, v221, v206, s[40:41]
	v_cndmask_b32_e64 v207, v207, v221, s[40:41]
	v_cndmask_b32_e64 v208, v222, v208, s[40:41]
	v_cndmask_b32_e64 v209, v209, v222, s[40:41]
	v_cndmask_b32_e64 v210, v223, v210, s[40:41]
	v_cndmask_b32_e64 v211, v211, v223, s[40:41]
	v_cndmask_b32_e64 v212, v224, v212, s[40:41]
	v_cndmask_b32_e64 v213, v213, v224, s[40:41]
	v_cndmask_b32_e64 v214, v225, v214, s[40:41]
	v_cndmask_b32_e64 v215, v215, v225, s[40:41]
	v_cndmask_b32_e64 v216, v226, v216, s[40:41]
	v_cndmask_b32_e64 v217, v217, v226, s[40:41]
	v_cndmask_b32_e64 v218, v227, v218, s[40:41]
	v_cndmask_b32_e64 v219, v219, v227, s[40:41]
	v_cvt_pk_bf16_f32 v204, v204, v205
	v_cvt_pk_bf16_f32 v206, v206, v207
	v_cvt_pk_bf16_f32 v208, v208, v209
	v_cvt_pk_bf16_f32 v210, v210, v211
	v_cvt_pk_bf16_f32 v212, v212, v213
	v_cvt_pk_bf16_f32 v214, v214, v215
	v_cvt_pk_bf16_f32 v216, v216, v217
	v_cvt_pk_bf16_f32 v218, v218, v219
	global_store_dword v236, v204, s[54:55]
	global_store_dword v236, v206, s[54:55] offset:64
	global_store_dword v237, v208, s[54:55]
	global_store_dword v237, v210, s[54:55] offset:64
	global_store_dword v238, v212, s[54:55]
	global_store_dword v238, v214, s[54:55] offset:64
	global_store_dword v239, v216, s[54:55]
	global_store_dword v239, v218, s[54:55] offset:64
	v_add_u32_e32 v245, 0x8000, v244
	v_add_u32_e32 v236, 0x8000, v249
	v_add_u32_e32 v246, 0x9000, v244
	v_add_u32_e32 v237, 0x9000, v249
	v_add_u32_e32 v247, 0xc000, v244
	v_add_u32_e32 v238, 0xc000, v249
	v_add_u32_e32 v248, 0xd000, v244
	v_add_u32_e32 v239, 0xd000, v249
	global_load_ushort v204, v245, s[52:53]
	global_load_ushort v205, v245, s[52:53] offset:2048
	global_load_ushort v206, v245, s[52:53] offset:64
	global_load_ushort v207, v245, s[52:53] offset:2112
	global_load_ushort v208, v246, s[52:53]
	global_load_ushort v209, v246, s[52:53] offset:2048
	global_load_ushort v210, v246, s[52:53] offset:64
	global_load_ushort v211, v246, s[52:53] offset:2112
	global_load_ushort v212, v247, s[52:53]
	global_load_ushort v213, v247, s[52:53] offset:2048
	global_load_ushort v214, v247, s[52:53] offset:64
	global_load_ushort v215, v247, s[52:53] offset:2112
	global_load_ushort v216, v248, s[52:53]
	global_load_ushort v217, v248, s[52:53] offset:2048
	global_load_ushort v218, v248, s[52:53] offset:64
	global_load_ushort v219, v248, s[52:53] offset:2112
	v_mul_f32_e32 v90, 0xbfb8aa3b, v90
	v_mul_f32_e32 v91, 0xbfb8aa3b, v91
	v_mul_f32_e32 v74, 0xbfb8aa3b, v74
	v_mul_f32_e32 v75, 0xbfb8aa3b, v75
	v_exp_f32_e32 v90, v90
	v_exp_f32_e32 v91, v91
	v_exp_f32_e32 v74, v74
	v_exp_f32_e32 v75, v75
	v_add_f32_e32 v90, 1.0, v90
	v_add_f32_e32 v91, 1.0, v91
	v_add_f32_e32 v74, 1.0, v74
	v_add_f32_e32 v75, 1.0, v75
	v_rcp_f32_e32 v90, v90
	v_rcp_f32_e32 v91, v91
	v_rcp_f32_e32 v74, v74
	v_rcp_f32_e32 v75, v75
	v_mul_f32_e32 v92, 0xbfb8aa3b, v92
	v_mul_f32_e32 v93, 0xbfb8aa3b, v93
	v_mul_f32_e32 v76, 0xbfb8aa3b, v76
	v_mul_f32_e32 v77, 0xbfb8aa3b, v77
	v_exp_f32_e32 v92, v92
	v_exp_f32_e32 v93, v93
	v_exp_f32_e32 v76, v76
	v_exp_f32_e32 v77, v77
	v_add_f32_e32 v92, 1.0, v92
	v_add_f32_e32 v93, 1.0, v93
	v_add_f32_e32 v76, 1.0, v76
	v_add_f32_e32 v77, 1.0, v77
	v_rcp_f32_e32 v92, v92
	v_rcp_f32_e32 v93, v93
	v_rcp_f32_e32 v76, v76
	v_rcp_f32_e32 v77, v77
	v_mul_f32_e32 v94, 0xbfb8aa3b, v94
	v_mul_f32_e32 v95, 0xbfb8aa3b, v95
	v_mul_f32_e32 v78, 0xbfb8aa3b, v78
	v_mul_f32_e32 v79, 0xbfb8aa3b, v79
	v_exp_f32_e32 v94, v94
	v_exp_f32_e32 v95, v95
	v_exp_f32_e32 v78, v78
	v_exp_f32_e32 v79, v79
	v_add_f32_e32 v94, 1.0, v94
	v_add_f32_e32 v95, 1.0, v95
	v_add_f32_e32 v78, 1.0, v78
	v_add_f32_e32 v79, 1.0, v79
	v_rcp_f32_e32 v94, v94
	v_rcp_f32_e32 v95, v95
	v_rcp_f32_e32 v78, v78
	v_rcp_f32_e32 v79, v79
	v_mul_f32_e32 v96, 0xbfb8aa3b, v96
	v_mul_f32_e32 v97, 0xbfb8aa3b, v97
	v_mul_f32_e32 v80, 0xbfb8aa3b, v80
	v_mul_f32_e32 v81, 0xbfb8aa3b, v81
	v_exp_f32_e32 v96, v96
	v_exp_f32_e32 v97, v97
	v_exp_f32_e32 v80, v80
	v_exp_f32_e32 v81, v81
	v_add_f32_e32 v96, 1.0, v96
	v_add_f32_e32 v97, 1.0, v97
	v_add_f32_e32 v80, 1.0, v80
	v_add_f32_e32 v81, 1.0, v81
	v_rcp_f32_e32 v96, v96
	v_rcp_f32_e32 v97, v97
	v_rcp_f32_e32 v80, v80
	v_rcp_f32_e32 v81, v81
	s_waitcnt vmcnt(0)
	v_lshlrev_b32_e32 v204, 16, v204
	v_lshlrev_b32_e32 v205, 16, v205
	v_lshlrev_b32_e32 v206, 16, v206
	v_lshlrev_b32_e32 v207, 16, v207
	v_lshlrev_b32_e32 v208, 16, v208
	v_lshlrev_b32_e32 v209, 16, v209
	v_lshlrev_b32_e32 v210, 16, v210
	v_lshlrev_b32_e32 v211, 16, v211
	v_lshlrev_b32_e32 v212, 16, v212
	v_lshlrev_b32_e32 v213, 16, v213
	v_lshlrev_b32_e32 v214, 16, v214
	v_lshlrev_b32_e32 v215, 16, v215
	v_lshlrev_b32_e32 v216, 16, v216
	v_lshlrev_b32_e32 v217, 16, v217
	v_lshlrev_b32_e32 v218, 16, v218
	v_lshlrev_b32_e32 v219, 16, v219
	v_mul_f32_e32 v204, v90, v204
	v_mul_f32_e32 v205, v91, v205
	v_mul_f32_e32 v206, v74, v206
	v_mul_f32_e32 v207, v75, v207
	v_mul_f32_e32 v208, v92, v208
	v_mul_f32_e32 v209, v93, v209
	v_mul_f32_e32 v210, v76, v210
	v_mul_f32_e32 v211, v77, v211
	v_mul_f32_e32 v212, v94, v212
	v_mul_f32_e32 v213, v95, v213
	v_mul_f32_e32 v214, v78, v214
	v_mul_f32_e32 v215, v79, v215
	v_mul_f32_e32 v216, v96, v216
	v_mul_f32_e32 v217, v97, v217
	v_mul_f32_e32 v218, v80, v218
	v_mul_f32_e32 v219, v81, v219
	v_cndmask_b32_e64 v220, v204, v205, s[40:41]
	v_cndmask_b32_e64 v221, v206, v207, s[40:41]
	v_cndmask_b32_e64 v222, v208, v209, s[40:41]
	v_cndmask_b32_e64 v223, v210, v211, s[40:41]
	v_cndmask_b32_e64 v224, v212, v213, s[40:41]
	v_cndmask_b32_e64 v225, v214, v215, s[40:41]
	v_cndmask_b32_e64 v226, v216, v217, s[40:41]
	v_cndmask_b32_e64 v227, v218, v219, s[40:41]
	v_mov_b32_dpp v220, v220 quad_perm:[1,0,3,2] row_mask:0xf bank_mask:0xf bound_ctrl:1
	v_mov_b32_dpp v221, v221 quad_perm:[1,0,3,2] row_mask:0xf bank_mask:0xf bound_ctrl:1
	v_mov_b32_dpp v222, v222 quad_perm:[1,0,3,2] row_mask:0xf bank_mask:0xf bound_ctrl:1
	v_mov_b32_dpp v223, v223 quad_perm:[1,0,3,2] row_mask:0xf bank_mask:0xf bound_ctrl:1
	v_mov_b32_dpp v224, v224 quad_perm:[1,0,3,2] row_mask:0xf bank_mask:0xf bound_ctrl:1
	v_mov_b32_dpp v225, v225 quad_perm:[1,0,3,2] row_mask:0xf bank_mask:0xf bound_ctrl:1
	v_mov_b32_dpp v226, v226 quad_perm:[1,0,3,2] row_mask:0xf bank_mask:0xf bound_ctrl:1
	v_mov_b32_dpp v227, v227 quad_perm:[1,0,3,2] row_mask:0xf bank_mask:0xf bound_ctrl:1
	v_cndmask_b32_e64 v204, v220, v204, s[40:41]
	v_cndmask_b32_e64 v205, v205, v220, s[40:41]
	v_cndmask_b32_e64 v206, v221, v206, s[40:41]
	v_cndmask_b32_e64 v207, v207, v221, s[40:41]
	v_cndmask_b32_e64 v208, v222, v208, s[40:41]
	v_cndmask_b32_e64 v209, v209, v222, s[40:41]
	v_cndmask_b32_e64 v210, v223, v210, s[40:41]
	v_cndmask_b32_e64 v211, v211, v223, s[40:41]
	v_cndmask_b32_e64 v212, v224, v212, s[40:41]
	v_cndmask_b32_e64 v213, v213, v224, s[40:41]
	v_cndmask_b32_e64 v214, v225, v214, s[40:41]
	v_cndmask_b32_e64 v215, v215, v225, s[40:41]
	v_cndmask_b32_e64 v216, v226, v216, s[40:41]
	v_cndmask_b32_e64 v217, v217, v226, s[40:41]
	v_cndmask_b32_e64 v218, v227, v218, s[40:41]
	v_cndmask_b32_e64 v219, v219, v227, s[40:41]
	v_cvt_pk_bf16_f32 v204, v204, v205
	v_cvt_pk_bf16_f32 v206, v206, v207
	v_cvt_pk_bf16_f32 v208, v208, v209
	v_cvt_pk_bf16_f32 v210, v210, v211
	v_cvt_pk_bf16_f32 v212, v212, v213
	v_cvt_pk_bf16_f32 v214, v214, v215
	v_cvt_pk_bf16_f32 v216, v216, v217
	v_cvt_pk_bf16_f32 v218, v218, v219
	global_store_dword v236, v204, s[54:55]
	global_store_dword v236, v206, s[54:55] offset:64
	global_store_dword v237, v208, s[54:55]
	global_store_dword v237, v210, s[54:55] offset:64
	global_store_dword v238, v212, s[54:55]
	global_store_dword v238, v214, s[54:55] offset:64
	global_store_dword v239, v216, s[54:55]
	global_store_dword v239, v218, s[54:55] offset:64
	v_add_u32_e32 v245, 0x10000, v244
	v_add_u32_e32 v236, 0x10000, v249
	v_add_u32_e32 v246, 0x11000, v244
	v_add_u32_e32 v237, 0x11000, v249
	v_add_u32_e32 v247, 0x14000, v244
	v_add_u32_e32 v238, 0x14000, v249
	v_add_u32_e32 v248, 0x15000, v244
	v_add_u32_e32 v239, 0x15000, v249
	global_load_ushort v204, v245, s[52:53]
	global_load_ushort v205, v245, s[52:53] offset:2048
	global_load_ushort v206, v245, s[52:53] offset:64
	global_load_ushort v207, v245, s[52:53] offset:2112
	global_load_ushort v208, v246, s[52:53]
	global_load_ushort v209, v246, s[52:53] offset:2048
	global_load_ushort v210, v246, s[52:53] offset:64
	global_load_ushort v211, v246, s[52:53] offset:2112
	global_load_ushort v212, v247, s[52:53]
	global_load_ushort v213, v247, s[52:53] offset:2048
	global_load_ushort v214, v247, s[52:53] offset:64
	global_load_ushort v215, v247, s[52:53] offset:2112
	global_load_ushort v216, v248, s[52:53]
	global_load_ushort v217, v248, s[52:53] offset:2048
	global_load_ushort v218, v248, s[52:53] offset:64
	global_load_ushort v219, v248, s[52:53] offset:2112
	v_mul_f32_e32 v50, 0xbfb8aa3b, v50
	v_mul_f32_e32 v51, 0xbfb8aa3b, v51
	v_mul_f32_e32 v34, 0xbfb8aa3b, v34
	v_mul_f32_e32 v35, 0xbfb8aa3b, v35
	v_exp_f32_e32 v50, v50
	v_exp_f32_e32 v51, v51
	v_exp_f32_e32 v34, v34
	v_exp_f32_e32 v35, v35
	v_add_f32_e32 v50, 1.0, v50
	v_add_f32_e32 v51, 1.0, v51
	v_add_f32_e32 v34, 1.0, v34
	v_add_f32_e32 v35, 1.0, v35
	v_rcp_f32_e32 v50, v50
	v_rcp_f32_e32 v51, v51
	v_rcp_f32_e32 v34, v34
	v_rcp_f32_e32 v35, v35
	v_mul_f32_e32 v52, 0xbfb8aa3b, v52
	v_mul_f32_e32 v53, 0xbfb8aa3b, v53
	v_mul_f32_e32 v36, 0xbfb8aa3b, v36
	v_mul_f32_e32 v37, 0xbfb8aa3b, v37
	v_exp_f32_e32 v52, v52
	v_exp_f32_e32 v53, v53
	v_exp_f32_e32 v36, v36
	v_exp_f32_e32 v37, v37
	v_add_f32_e32 v52, 1.0, v52
	v_add_f32_e32 v53, 1.0, v53
	v_add_f32_e32 v36, 1.0, v36
	v_add_f32_e32 v37, 1.0, v37
	v_rcp_f32_e32 v52, v52
	v_rcp_f32_e32 v53, v53
	v_rcp_f32_e32 v36, v36
	v_rcp_f32_e32 v37, v37
	v_mul_f32_e32 v54, 0xbfb8aa3b, v54
	v_mul_f32_e32 v55, 0xbfb8aa3b, v55
	v_mul_f32_e32 v38, 0xbfb8aa3b, v38
	v_mul_f32_e32 v39, 0xbfb8aa3b, v39
	v_exp_f32_e32 v54, v54
	v_exp_f32_e32 v55, v55
	v_exp_f32_e32 v38, v38
	v_exp_f32_e32 v39, v39
	v_add_f32_e32 v54, 1.0, v54
	v_add_f32_e32 v55, 1.0, v55
	v_add_f32_e32 v38, 1.0, v38
	v_add_f32_e32 v39, 1.0, v39
	v_rcp_f32_e32 v54, v54
	v_rcp_f32_e32 v55, v55
	v_rcp_f32_e32 v38, v38
	v_rcp_f32_e32 v39, v39
	v_mul_f32_e32 v56, 0xbfb8aa3b, v56
	v_mul_f32_e32 v57, 0xbfb8aa3b, v57
	v_mul_f32_e32 v40, 0xbfb8aa3b, v40
	v_mul_f32_e32 v41, 0xbfb8aa3b, v41
	v_exp_f32_e32 v56, v56
	v_exp_f32_e32 v57, v57
	v_exp_f32_e32 v40, v40
	v_exp_f32_e32 v41, v41
	v_add_f32_e32 v56, 1.0, v56
	v_add_f32_e32 v57, 1.0, v57
	v_add_f32_e32 v40, 1.0, v40
	v_add_f32_e32 v41, 1.0, v41
	v_rcp_f32_e32 v56, v56
	v_rcp_f32_e32 v57, v57
	v_rcp_f32_e32 v40, v40
	v_rcp_f32_e32 v41, v41
	s_waitcnt vmcnt(0)
	v_lshlrev_b32_e32 v204, 16, v204
	v_lshlrev_b32_e32 v205, 16, v205
	v_lshlrev_b32_e32 v206, 16, v206
	v_lshlrev_b32_e32 v207, 16, v207
	v_lshlrev_b32_e32 v208, 16, v208
	v_lshlrev_b32_e32 v209, 16, v209
	v_lshlrev_b32_e32 v210, 16, v210
	v_lshlrev_b32_e32 v211, 16, v211
	v_lshlrev_b32_e32 v212, 16, v212
	v_lshlrev_b32_e32 v213, 16, v213
	v_lshlrev_b32_e32 v214, 16, v214
	v_lshlrev_b32_e32 v215, 16, v215
	v_lshlrev_b32_e32 v216, 16, v216
	v_lshlrev_b32_e32 v217, 16, v217
	v_lshlrev_b32_e32 v218, 16, v218
	v_lshlrev_b32_e32 v219, 16, v219
	v_mul_f32_e32 v204, v50, v204
	v_mul_f32_e32 v205, v51, v205
	v_mul_f32_e32 v206, v34, v206
	v_mul_f32_e32 v207, v35, v207
	v_mul_f32_e32 v208, v52, v208
	v_mul_f32_e32 v209, v53, v209
	v_mul_f32_e32 v210, v36, v210
	v_mul_f32_e32 v211, v37, v211
	v_mul_f32_e32 v212, v54, v212
	v_mul_f32_e32 v213, v55, v213
	v_mul_f32_e32 v214, v38, v214
	v_mul_f32_e32 v215, v39, v215
	v_mul_f32_e32 v216, v56, v216
	v_mul_f32_e32 v217, v57, v217
	v_mul_f32_e32 v218, v40, v218
	v_mul_f32_e32 v219, v41, v219
	v_cndmask_b32_e64 v220, v204, v205, s[40:41]
	v_cndmask_b32_e64 v221, v206, v207, s[40:41]
	v_cndmask_b32_e64 v222, v208, v209, s[40:41]
	v_cndmask_b32_e64 v223, v210, v211, s[40:41]
	v_cndmask_b32_e64 v224, v212, v213, s[40:41]
	v_cndmask_b32_e64 v225, v214, v215, s[40:41]
	v_cndmask_b32_e64 v226, v216, v217, s[40:41]
	v_cndmask_b32_e64 v227, v218, v219, s[40:41]
	v_mov_b32_dpp v220, v220 quad_perm:[1,0,3,2] row_mask:0xf bank_mask:0xf bound_ctrl:1
	v_mov_b32_dpp v221, v221 quad_perm:[1,0,3,2] row_mask:0xf bank_mask:0xf bound_ctrl:1
	v_mov_b32_dpp v222, v222 quad_perm:[1,0,3,2] row_mask:0xf bank_mask:0xf bound_ctrl:1
	v_mov_b32_dpp v223, v223 quad_perm:[1,0,3,2] row_mask:0xf bank_mask:0xf bound_ctrl:1
	v_mov_b32_dpp v224, v224 quad_perm:[1,0,3,2] row_mask:0xf bank_mask:0xf bound_ctrl:1
	v_mov_b32_dpp v225, v225 quad_perm:[1,0,3,2] row_mask:0xf bank_mask:0xf bound_ctrl:1
	v_mov_b32_dpp v226, v226 quad_perm:[1,0,3,2] row_mask:0xf bank_mask:0xf bound_ctrl:1
	v_mov_b32_dpp v227, v227 quad_perm:[1,0,3,2] row_mask:0xf bank_mask:0xf bound_ctrl:1
	v_cndmask_b32_e64 v204, v220, v204, s[40:41]
	v_cndmask_b32_e64 v205, v205, v220, s[40:41]
	v_cndmask_b32_e64 v206, v221, v206, s[40:41]
	v_cndmask_b32_e64 v207, v207, v221, s[40:41]
	v_cndmask_b32_e64 v208, v222, v208, s[40:41]
	v_cndmask_b32_e64 v209, v209, v222, s[40:41]
	v_cndmask_b32_e64 v210, v223, v210, s[40:41]
	v_cndmask_b32_e64 v211, v211, v223, s[40:41]
	v_cndmask_b32_e64 v212, v224, v212, s[40:41]
	v_cndmask_b32_e64 v213, v213, v224, s[40:41]
	v_cndmask_b32_e64 v214, v225, v214, s[40:41]
	v_cndmask_b32_e64 v215, v215, v225, s[40:41]
	v_cndmask_b32_e64 v216, v226, v216, s[40:41]
	v_cndmask_b32_e64 v217, v217, v226, s[40:41]
	v_cndmask_b32_e64 v218, v227, v218, s[40:41]
	v_cndmask_b32_e64 v219, v219, v227, s[40:41]
	v_cvt_pk_bf16_f32 v204, v204, v205
	v_cvt_pk_bf16_f32 v206, v206, v207
	v_cvt_pk_bf16_f32 v208, v208, v209
	v_cvt_pk_bf16_f32 v210, v210, v211
	v_cvt_pk_bf16_f32 v212, v212, v213
	v_cvt_pk_bf16_f32 v214, v214, v215
	v_cvt_pk_bf16_f32 v216, v216, v217
	v_cvt_pk_bf16_f32 v218, v218, v219
	global_store_dword v236, v204, s[54:55]
	global_store_dword v236, v206, s[54:55] offset:64
	global_store_dword v237, v208, s[54:55]
	global_store_dword v237, v210, s[54:55] offset:64
	global_store_dword v238, v212, s[54:55]
	global_store_dword v238, v214, s[54:55] offset:64
	global_store_dword v239, v216, s[54:55]
	global_store_dword v239, v218, s[54:55] offset:64
	v_add_u32_e32 v245, 0x18000, v244
	v_add_u32_e32 v236, 0x18000, v249
	v_add_u32_e32 v246, 0x19000, v244
	v_add_u32_e32 v237, 0x19000, v249
	v_add_u32_e32 v247, 0x1c000, v244
	v_add_u32_e32 v238, 0x1c000, v249
	v_add_u32_e32 v248, 0x1d000, v244
	v_add_u32_e32 v239, 0x1d000, v249
	global_load_ushort v204, v245, s[52:53]
	global_load_ushort v205, v245, s[52:53] offset:2048
	global_load_ushort v206, v245, s[52:53] offset:64
	global_load_ushort v207, v245, s[52:53] offset:2112
	global_load_ushort v208, v246, s[52:53]
	global_load_ushort v209, v246, s[52:53] offset:2048
	global_load_ushort v210, v246, s[52:53] offset:64
	global_load_ushort v211, v246, s[52:53] offset:2112
	global_load_ushort v212, v247, s[52:53]
	global_load_ushort v213, v247, s[52:53] offset:2048
	global_load_ushort v214, v247, s[52:53] offset:64
	global_load_ushort v215, v247, s[52:53] offset:2112
	global_load_ushort v216, v248, s[52:53]
	global_load_ushort v217, v248, s[52:53] offset:2048
	global_load_ushort v218, v248, s[52:53] offset:64
	global_load_ushort v219, v248, s[52:53] offset:2112
	v_mul_f32_e32 v58, 0xbfb8aa3b, v58
	v_mul_f32_e32 v59, 0xbfb8aa3b, v59
	v_mul_f32_e32 v42, 0xbfb8aa3b, v42
	v_mul_f32_e32 v43, 0xbfb8aa3b, v43
	v_exp_f32_e32 v58, v58
	v_exp_f32_e32 v59, v59
	v_exp_f32_e32 v42, v42
	v_exp_f32_e32 v43, v43
	v_add_f32_e32 v58, 1.0, v58
	v_add_f32_e32 v59, 1.0, v59
	v_add_f32_e32 v42, 1.0, v42
	v_add_f32_e32 v43, 1.0, v43
	v_rcp_f32_e32 v58, v58
	v_rcp_f32_e32 v59, v59
	v_rcp_f32_e32 v42, v42
	v_rcp_f32_e32 v43, v43
	v_mul_f32_e32 v60, 0xbfb8aa3b, v60
	v_mul_f32_e32 v61, 0xbfb8aa3b, v61
	v_mul_f32_e32 v44, 0xbfb8aa3b, v44
	v_mul_f32_e32 v45, 0xbfb8aa3b, v45
	v_exp_f32_e32 v60, v60
	v_exp_f32_e32 v61, v61
	v_exp_f32_e32 v44, v44
	v_exp_f32_e32 v45, v45
	v_add_f32_e32 v60, 1.0, v60
	v_add_f32_e32 v61, 1.0, v61
	v_add_f32_e32 v44, 1.0, v44
	v_add_f32_e32 v45, 1.0, v45
	v_rcp_f32_e32 v60, v60
	v_rcp_f32_e32 v61, v61
	v_rcp_f32_e32 v44, v44
	v_rcp_f32_e32 v45, v45
	v_mul_f32_e32 v62, 0xbfb8aa3b, v62
	v_mul_f32_e32 v63, 0xbfb8aa3b, v63
	v_mul_f32_e32 v46, 0xbfb8aa3b, v46
	v_mul_f32_e32 v47, 0xbfb8aa3b, v47
	v_exp_f32_e32 v62, v62
	v_exp_f32_e32 v63, v63
	v_exp_f32_e32 v46, v46
	v_exp_f32_e32 v47, v47
	v_add_f32_e32 v62, 1.0, v62
	v_add_f32_e32 v63, 1.0, v63
	v_add_f32_e32 v46, 1.0, v46
	v_add_f32_e32 v47, 1.0, v47
	v_rcp_f32_e32 v62, v62
	v_rcp_f32_e32 v63, v63
	v_rcp_f32_e32 v46, v46
	v_rcp_f32_e32 v47, v47
	v_mul_f32_e32 v64, 0xbfb8aa3b, v64
	v_mul_f32_e32 v65, 0xbfb8aa3b, v65
	v_mul_f32_e32 v48, 0xbfb8aa3b, v48
	v_mul_f32_e32 v49, 0xbfb8aa3b, v49
	v_exp_f32_e32 v64, v64
	v_exp_f32_e32 v65, v65
	v_exp_f32_e32 v48, v48
	v_exp_f32_e32 v49, v49
	v_add_f32_e32 v64, 1.0, v64
	v_add_f32_e32 v65, 1.0, v65
	v_add_f32_e32 v48, 1.0, v48
	v_add_f32_e32 v49, 1.0, v49
	v_rcp_f32_e32 v64, v64
	v_rcp_f32_e32 v65, v65
	v_rcp_f32_e32 v48, v48
	v_rcp_f32_e32 v49, v49
	s_waitcnt vmcnt(0)
	v_lshlrev_b32_e32 v204, 16, v204
	v_lshlrev_b32_e32 v205, 16, v205
	v_lshlrev_b32_e32 v206, 16, v206
	v_lshlrev_b32_e32 v207, 16, v207
	v_lshlrev_b32_e32 v208, 16, v208
	v_lshlrev_b32_e32 v209, 16, v209
	v_lshlrev_b32_e32 v210, 16, v210
	v_lshlrev_b32_e32 v211, 16, v211
	v_lshlrev_b32_e32 v212, 16, v212
	v_lshlrev_b32_e32 v213, 16, v213
	v_lshlrev_b32_e32 v214, 16, v214
	v_lshlrev_b32_e32 v215, 16, v215
	v_lshlrev_b32_e32 v216, 16, v216
	v_lshlrev_b32_e32 v217, 16, v217
	v_lshlrev_b32_e32 v218, 16, v218
	v_lshlrev_b32_e32 v219, 16, v219
	v_mul_f32_e32 v204, v58, v204
	v_mul_f32_e32 v205, v59, v205
	v_mul_f32_e32 v206, v42, v206
	v_mul_f32_e32 v207, v43, v207
	v_mul_f32_e32 v208, v60, v208
	v_mul_f32_e32 v209, v61, v209
	v_mul_f32_e32 v210, v44, v210
	v_mul_f32_e32 v211, v45, v211
	v_mul_f32_e32 v212, v62, v212
	v_mul_f32_e32 v213, v63, v213
	v_mul_f32_e32 v214, v46, v214
	v_mul_f32_e32 v215, v47, v215
	v_mul_f32_e32 v216, v64, v216
	v_mul_f32_e32 v217, v65, v217
	v_mul_f32_e32 v218, v48, v218
	v_mul_f32_e32 v219, v49, v219
	v_cndmask_b32_e64 v220, v204, v205, s[40:41]
	v_cndmask_b32_e64 v221, v206, v207, s[40:41]
	v_cndmask_b32_e64 v222, v208, v209, s[40:41]
	v_cndmask_b32_e64 v223, v210, v211, s[40:41]
	v_cndmask_b32_e64 v224, v212, v213, s[40:41]
	v_cndmask_b32_e64 v225, v214, v215, s[40:41]
	v_cndmask_b32_e64 v226, v216, v217, s[40:41]
	v_cndmask_b32_e64 v227, v218, v219, s[40:41]
	v_mov_b32_dpp v220, v220 quad_perm:[1,0,3,2] row_mask:0xf bank_mask:0xf bound_ctrl:1
	v_mov_b32_dpp v221, v221 quad_perm:[1,0,3,2] row_mask:0xf bank_mask:0xf bound_ctrl:1
	v_mov_b32_dpp v222, v222 quad_perm:[1,0,3,2] row_mask:0xf bank_mask:0xf bound_ctrl:1
	v_mov_b32_dpp v223, v223 quad_perm:[1,0,3,2] row_mask:0xf bank_mask:0xf bound_ctrl:1
	v_mov_b32_dpp v224, v224 quad_perm:[1,0,3,2] row_mask:0xf bank_mask:0xf bound_ctrl:1
	v_mov_b32_dpp v225, v225 quad_perm:[1,0,3,2] row_mask:0xf bank_mask:0xf bound_ctrl:1
	v_mov_b32_dpp v226, v226 quad_perm:[1,0,3,2] row_mask:0xf bank_mask:0xf bound_ctrl:1
	v_mov_b32_dpp v227, v227 quad_perm:[1,0,3,2] row_mask:0xf bank_mask:0xf bound_ctrl:1
	v_cndmask_b32_e64 v204, v220, v204, s[40:41]
	v_cndmask_b32_e64 v205, v205, v220, s[40:41]
	v_cndmask_b32_e64 v206, v221, v206, s[40:41]
	v_cndmask_b32_e64 v207, v207, v221, s[40:41]
	v_cndmask_b32_e64 v208, v222, v208, s[40:41]
	v_cndmask_b32_e64 v209, v209, v222, s[40:41]
	v_cndmask_b32_e64 v210, v223, v210, s[40:41]
	v_cndmask_b32_e64 v211, v211, v223, s[40:41]
	v_cndmask_b32_e64 v212, v224, v212, s[40:41]
	v_cndmask_b32_e64 v213, v213, v224, s[40:41]
	v_cndmask_b32_e64 v214, v225, v214, s[40:41]
	v_cndmask_b32_e64 v215, v215, v225, s[40:41]
	v_cndmask_b32_e64 v216, v226, v216, s[40:41]
	v_cndmask_b32_e64 v217, v217, v226, s[40:41]
	v_cndmask_b32_e64 v218, v227, v218, s[40:41]
	v_cndmask_b32_e64 v219, v219, v227, s[40:41]
	v_cvt_pk_bf16_f32 v204, v204, v205
	v_cvt_pk_bf16_f32 v206, v206, v207
	v_cvt_pk_bf16_f32 v208, v208, v209
	v_cvt_pk_bf16_f32 v210, v210, v211
	v_cvt_pk_bf16_f32 v212, v212, v213
	v_cvt_pk_bf16_f32 v214, v214, v215
	v_cvt_pk_bf16_f32 v216, v216, v217
	v_cvt_pk_bf16_f32 v218, v218, v219
	global_store_dword v236, v204, s[54:55]
	global_store_dword v236, v206, s[54:55] offset:64
	global_store_dword v237, v208, s[54:55]
	global_store_dword v237, v210, s[54:55] offset:64
	global_store_dword v238, v212, s[54:55]
	global_store_dword v238, v214, s[54:55] offset:64
	global_store_dword v239, v216, s[54:55]
	global_store_dword v239, v218, s[54:55] offset:64
	v_add_u32_e32 v245, 0x20000, v244
	v_add_u32_e32 v236, 0x20000, v249
	v_add_u32_e32 v246, 0x21000, v244
	v_add_u32_e32 v237, 0x21000, v249
	v_add_u32_e32 v247, 0x24000, v244
	v_add_u32_e32 v238, 0x24000, v249
	v_add_u32_e32 v248, 0x25000, v244
	v_add_u32_e32 v239, 0x25000, v249
	global_load_ushort v204, v245, s[52:53]
	global_load_ushort v205, v245, s[52:53] offset:2048
	global_load_ushort v206, v245, s[52:53] offset:64
	global_load_ushort v207, v245, s[52:53] offset:2112
	global_load_ushort v208, v246, s[52:53]
	global_load_ushort v209, v246, s[52:53] offset:2048
	global_load_ushort v210, v246, s[52:53] offset:64
	global_load_ushort v211, v246, s[52:53] offset:2112
	global_load_ushort v212, v247, s[52:53]
	global_load_ushort v213, v247, s[52:53] offset:2048
	global_load_ushort v214, v247, s[52:53] offset:64
	global_load_ushort v215, v247, s[52:53] offset:2112
	global_load_ushort v216, v248, s[52:53]
	global_load_ushort v217, v248, s[52:53] offset:2048
	global_load_ushort v218, v248, s[52:53] offset:64
	global_load_ushort v219, v248, s[52:53] offset:2112
	v_mul_f32_e32 v18, 0xbfb8aa3b, v18
	v_mul_f32_e32 v19, 0xbfb8aa3b, v19
	v_mul_f32_e32 v2, 0xbfb8aa3b, v2
	v_mul_f32_e32 v3, 0xbfb8aa3b, v3
	v_exp_f32_e32 v18, v18
	v_exp_f32_e32 v19, v19
	v_exp_f32_e32 v2, v2
	v_exp_f32_e32 v3, v3
	v_add_f32_e32 v18, 1.0, v18
	v_add_f32_e32 v19, 1.0, v19
	v_add_f32_e32 v2, 1.0, v2
	v_add_f32_e32 v3, 1.0, v3
	v_rcp_f32_e32 v18, v18
	v_rcp_f32_e32 v19, v19
	v_rcp_f32_e32 v2, v2
	v_rcp_f32_e32 v3, v3
	v_mul_f32_e32 v20, 0xbfb8aa3b, v20
	v_mul_f32_e32 v21, 0xbfb8aa3b, v21
	v_mul_f32_e32 v4, 0xbfb8aa3b, v4
	v_mul_f32_e32 v5, 0xbfb8aa3b, v5
	v_exp_f32_e32 v20, v20
	v_exp_f32_e32 v21, v21
	v_exp_f32_e32 v4, v4
	v_exp_f32_e32 v5, v5
	v_add_f32_e32 v20, 1.0, v20
	v_add_f32_e32 v21, 1.0, v21
	v_add_f32_e32 v4, 1.0, v4
	v_add_f32_e32 v5, 1.0, v5
	v_rcp_f32_e32 v20, v20
	v_rcp_f32_e32 v21, v21
	v_rcp_f32_e32 v4, v4
	v_rcp_f32_e32 v5, v5
	v_mul_f32_e32 v22, 0xbfb8aa3b, v22
	v_mul_f32_e32 v23, 0xbfb8aa3b, v23
	v_mul_f32_e32 v6, 0xbfb8aa3b, v6
	v_mul_f32_e32 v7, 0xbfb8aa3b, v7
	v_exp_f32_e32 v22, v22
	v_exp_f32_e32 v23, v23
	v_exp_f32_e32 v6, v6
	v_exp_f32_e32 v7, v7
	v_add_f32_e32 v22, 1.0, v22
	v_add_f32_e32 v23, 1.0, v23
	v_add_f32_e32 v6, 1.0, v6
	v_add_f32_e32 v7, 1.0, v7
	v_rcp_f32_e32 v22, v22
	v_rcp_f32_e32 v23, v23
	v_rcp_f32_e32 v6, v6
	v_rcp_f32_e32 v7, v7
	v_mul_f32_e32 v24, 0xbfb8aa3b, v24
	v_mul_f32_e32 v25, 0xbfb8aa3b, v25
	v_mul_f32_e32 v8, 0xbfb8aa3b, v8
	v_mul_f32_e32 v9, 0xbfb8aa3b, v9
	v_exp_f32_e32 v24, v24
	v_exp_f32_e32 v25, v25
	v_exp_f32_e32 v8, v8
	v_exp_f32_e32 v9, v9
	v_add_f32_e32 v24, 1.0, v24
	v_add_f32_e32 v25, 1.0, v25
	v_add_f32_e32 v8, 1.0, v8
	v_add_f32_e32 v9, 1.0, v9
	v_rcp_f32_e32 v24, v24
	v_rcp_f32_e32 v25, v25
	v_rcp_f32_e32 v8, v8
	v_rcp_f32_e32 v9, v9
	s_waitcnt vmcnt(0)
	v_lshlrev_b32_e32 v204, 16, v204
	v_lshlrev_b32_e32 v205, 16, v205
	v_lshlrev_b32_e32 v206, 16, v206
	v_lshlrev_b32_e32 v207, 16, v207
	v_lshlrev_b32_e32 v208, 16, v208
	v_lshlrev_b32_e32 v209, 16, v209
	v_lshlrev_b32_e32 v210, 16, v210
	v_lshlrev_b32_e32 v211, 16, v211
	v_lshlrev_b32_e32 v212, 16, v212
	v_lshlrev_b32_e32 v213, 16, v213
	v_lshlrev_b32_e32 v214, 16, v214
	v_lshlrev_b32_e32 v215, 16, v215
	v_lshlrev_b32_e32 v216, 16, v216
	v_lshlrev_b32_e32 v217, 16, v217
	v_lshlrev_b32_e32 v218, 16, v218
	v_lshlrev_b32_e32 v219, 16, v219
	v_mul_f32_e32 v204, v18, v204
	v_mul_f32_e32 v205, v19, v205
	v_mul_f32_e32 v206, v2, v206
	v_mul_f32_e32 v207, v3, v207
	v_mul_f32_e32 v208, v20, v208
	v_mul_f32_e32 v209, v21, v209
	v_mul_f32_e32 v210, v4, v210
	v_mul_f32_e32 v211, v5, v211
	v_mul_f32_e32 v212, v22, v212
	v_mul_f32_e32 v213, v23, v213
	v_mul_f32_e32 v214, v6, v214
	v_mul_f32_e32 v215, v7, v215
	v_mul_f32_e32 v216, v24, v216
	v_mul_f32_e32 v217, v25, v217
	v_mul_f32_e32 v218, v8, v218
	v_mul_f32_e32 v219, v9, v219
	v_cndmask_b32_e64 v220, v204, v205, s[40:41]
	v_cndmask_b32_e64 v221, v206, v207, s[40:41]
	v_cndmask_b32_e64 v222, v208, v209, s[40:41]
	v_cndmask_b32_e64 v223, v210, v211, s[40:41]
	v_cndmask_b32_e64 v224, v212, v213, s[40:41]
	v_cndmask_b32_e64 v225, v214, v215, s[40:41]
	v_cndmask_b32_e64 v226, v216, v217, s[40:41]
	v_cndmask_b32_e64 v227, v218, v219, s[40:41]
	v_mov_b32_dpp v220, v220 quad_perm:[1,0,3,2] row_mask:0xf bank_mask:0xf bound_ctrl:1
	v_mov_b32_dpp v221, v221 quad_perm:[1,0,3,2] row_mask:0xf bank_mask:0xf bound_ctrl:1
	v_mov_b32_dpp v222, v222 quad_perm:[1,0,3,2] row_mask:0xf bank_mask:0xf bound_ctrl:1
	v_mov_b32_dpp v223, v223 quad_perm:[1,0,3,2] row_mask:0xf bank_mask:0xf bound_ctrl:1
	v_mov_b32_dpp v224, v224 quad_perm:[1,0,3,2] row_mask:0xf bank_mask:0xf bound_ctrl:1
	v_mov_b32_dpp v225, v225 quad_perm:[1,0,3,2] row_mask:0xf bank_mask:0xf bound_ctrl:1
	v_mov_b32_dpp v226, v226 quad_perm:[1,0,3,2] row_mask:0xf bank_mask:0xf bound_ctrl:1
	v_mov_b32_dpp v227, v227 quad_perm:[1,0,3,2] row_mask:0xf bank_mask:0xf bound_ctrl:1
	v_cndmask_b32_e64 v204, v220, v204, s[40:41]
	v_cndmask_b32_e64 v205, v205, v220, s[40:41]
	v_cndmask_b32_e64 v206, v221, v206, s[40:41]
	v_cndmask_b32_e64 v207, v207, v221, s[40:41]
	v_cndmask_b32_e64 v208, v222, v208, s[40:41]
	v_cndmask_b32_e64 v209, v209, v222, s[40:41]
	v_cndmask_b32_e64 v210, v223, v210, s[40:41]
	v_cndmask_b32_e64 v211, v211, v223, s[40:41]
	v_cndmask_b32_e64 v212, v224, v212, s[40:41]
	v_cndmask_b32_e64 v213, v213, v224, s[40:41]
	v_cndmask_b32_e64 v214, v225, v214, s[40:41]
	v_cndmask_b32_e64 v215, v215, v225, s[40:41]
	v_cndmask_b32_e64 v216, v226, v216, s[40:41]
	v_cndmask_b32_e64 v217, v217, v226, s[40:41]
	v_cndmask_b32_e64 v218, v227, v218, s[40:41]
	v_cndmask_b32_e64 v219, v219, v227, s[40:41]
	v_cvt_pk_bf16_f32 v204, v204, v205
	v_cvt_pk_bf16_f32 v206, v206, v207
	v_cvt_pk_bf16_f32 v208, v208, v209
	v_cvt_pk_bf16_f32 v210, v210, v211
	v_cvt_pk_bf16_f32 v212, v212, v213
	v_cvt_pk_bf16_f32 v214, v214, v215
	v_cvt_pk_bf16_f32 v216, v216, v217
	v_cvt_pk_bf16_f32 v218, v218, v219
	global_store_dword v236, v204, s[54:55]
	global_store_dword v236, v206, s[54:55] offset:64
	global_store_dword v237, v208, s[54:55]
	global_store_dword v237, v210, s[54:55] offset:64
	global_store_dword v238, v212, s[54:55]
	global_store_dword v238, v214, s[54:55] offset:64
	global_store_dword v239, v216, s[54:55]
	global_store_dword v239, v218, s[54:55] offset:64
	v_add_u32_e32 v245, 0x28000, v244
	v_add_u32_e32 v236, 0x28000, v249
	v_add_u32_e32 v246, 0x29000, v244
	v_add_u32_e32 v237, 0x29000, v249
	v_add_u32_e32 v247, 0x2c000, v244
	v_add_u32_e32 v238, 0x2c000, v249
	v_add_u32_e32 v248, 0x2d000, v244
	v_add_u32_e32 v239, 0x2d000, v249
	global_load_ushort v204, v245, s[52:53]
	global_load_ushort v205, v245, s[52:53] offset:2048
	global_load_ushort v206, v245, s[52:53] offset:64
	global_load_ushort v207, v245, s[52:53] offset:2112
	global_load_ushort v208, v246, s[52:53]
	global_load_ushort v209, v246, s[52:53] offset:2048
	global_load_ushort v210, v246, s[52:53] offset:64
	global_load_ushort v211, v246, s[52:53] offset:2112
	global_load_ushort v212, v247, s[52:53]
	global_load_ushort v213, v247, s[52:53] offset:2048
	global_load_ushort v214, v247, s[52:53] offset:64
	global_load_ushort v215, v247, s[52:53] offset:2112
	global_load_ushort v216, v248, s[52:53]
	global_load_ushort v217, v248, s[52:53] offset:2048
	global_load_ushort v218, v248, s[52:53] offset:64
	global_load_ushort v219, v248, s[52:53] offset:2112
	v_mul_f32_e32 v26, 0xbfb8aa3b, v26
	v_mul_f32_e32 v27, 0xbfb8aa3b, v27
	v_mul_f32_e32 v10, 0xbfb8aa3b, v10
	v_mul_f32_e32 v11, 0xbfb8aa3b, v11
	v_exp_f32_e32 v26, v26
	v_exp_f32_e32 v27, v27
	v_exp_f32_e32 v10, v10
	v_exp_f32_e32 v11, v11
	v_add_f32_e32 v26, 1.0, v26
	v_add_f32_e32 v27, 1.0, v27
	v_add_f32_e32 v10, 1.0, v10
	v_add_f32_e32 v11, 1.0, v11
	v_rcp_f32_e32 v26, v26
	v_rcp_f32_e32 v27, v27
	v_rcp_f32_e32 v10, v10
	v_rcp_f32_e32 v11, v11
	v_mul_f32_e32 v28, 0xbfb8aa3b, v28
	v_mul_f32_e32 v29, 0xbfb8aa3b, v29
	v_mul_f32_e32 v12, 0xbfb8aa3b, v12
	v_mul_f32_e32 v13, 0xbfb8aa3b, v13
	v_exp_f32_e32 v28, v28
	v_exp_f32_e32 v29, v29
	v_exp_f32_e32 v12, v12
	v_exp_f32_e32 v13, v13
	v_add_f32_e32 v28, 1.0, v28
	v_add_f32_e32 v29, 1.0, v29
	v_add_f32_e32 v12, 1.0, v12
	v_add_f32_e32 v13, 1.0, v13
	v_rcp_f32_e32 v28, v28
	v_rcp_f32_e32 v29, v29
	v_rcp_f32_e32 v12, v12
	v_rcp_f32_e32 v13, v13
	v_mul_f32_e32 v30, 0xbfb8aa3b, v30
	v_mul_f32_e32 v31, 0xbfb8aa3b, v31
	v_mul_f32_e32 v14, 0xbfb8aa3b, v14
	v_mul_f32_e32 v15, 0xbfb8aa3b, v15
	v_exp_f32_e32 v30, v30
	v_exp_f32_e32 v31, v31
	v_exp_f32_e32 v14, v14
	v_exp_f32_e32 v15, v15
	v_add_f32_e32 v30, 1.0, v30
	v_add_f32_e32 v31, 1.0, v31
	v_add_f32_e32 v14, 1.0, v14
	v_add_f32_e32 v15, 1.0, v15
	v_rcp_f32_e32 v30, v30
	v_rcp_f32_e32 v31, v31
	v_rcp_f32_e32 v14, v14
	v_rcp_f32_e32 v15, v15
	v_mul_f32_e32 v32, 0xbfb8aa3b, v32
	v_mul_f32_e32 v33, 0xbfb8aa3b, v33
	v_mul_f32_e32 v16, 0xbfb8aa3b, v16
	v_mul_f32_e32 v17, 0xbfb8aa3b, v17
	v_exp_f32_e32 v32, v32
	v_exp_f32_e32 v33, v33
	v_exp_f32_e32 v16, v16
	v_exp_f32_e32 v17, v17
	v_add_f32_e32 v32, 1.0, v32
	v_add_f32_e32 v33, 1.0, v33
	v_add_f32_e32 v16, 1.0, v16
	v_add_f32_e32 v17, 1.0, v17
	v_rcp_f32_e32 v32, v32
	v_rcp_f32_e32 v33, v33
	v_rcp_f32_e32 v16, v16
	v_rcp_f32_e32 v17, v17
	s_waitcnt vmcnt(0)
	v_lshlrev_b32_e32 v204, 16, v204
	v_lshlrev_b32_e32 v205, 16, v205
	v_lshlrev_b32_e32 v206, 16, v206
	v_lshlrev_b32_e32 v207, 16, v207
	v_lshlrev_b32_e32 v208, 16, v208
	v_lshlrev_b32_e32 v209, 16, v209
	v_lshlrev_b32_e32 v210, 16, v210
	v_lshlrev_b32_e32 v211, 16, v211
	v_lshlrev_b32_e32 v212, 16, v212
	v_lshlrev_b32_e32 v213, 16, v213
	v_lshlrev_b32_e32 v214, 16, v214
	v_lshlrev_b32_e32 v215, 16, v215
	v_lshlrev_b32_e32 v216, 16, v216
	v_lshlrev_b32_e32 v217, 16, v217
	v_lshlrev_b32_e32 v218, 16, v218
	v_lshlrev_b32_e32 v219, 16, v219
	v_mul_f32_e32 v204, v26, v204
	v_mul_f32_e32 v205, v27, v205
	v_mul_f32_e32 v206, v10, v206
	v_mul_f32_e32 v207, v11, v207
	v_mul_f32_e32 v208, v28, v208
	v_mul_f32_e32 v209, v29, v209
	v_mul_f32_e32 v210, v12, v210
	v_mul_f32_e32 v211, v13, v211
	v_mul_f32_e32 v212, v30, v212
	v_mul_f32_e32 v213, v31, v213
	v_mul_f32_e32 v214, v14, v214
	v_mul_f32_e32 v215, v15, v215
	v_mul_f32_e32 v216, v32, v216
	v_mul_f32_e32 v217, v33, v217
	v_mul_f32_e32 v218, v16, v218
	v_mul_f32_e32 v219, v17, v219
	v_cndmask_b32_e64 v220, v204, v205, s[40:41]
	v_cndmask_b32_e64 v221, v206, v207, s[40:41]
	v_cndmask_b32_e64 v222, v208, v209, s[40:41]
	v_cndmask_b32_e64 v223, v210, v211, s[40:41]
	v_cndmask_b32_e64 v224, v212, v213, s[40:41]
	v_cndmask_b32_e64 v225, v214, v215, s[40:41]
	v_cndmask_b32_e64 v226, v216, v217, s[40:41]
	v_cndmask_b32_e64 v227, v218, v219, s[40:41]
	v_mov_b32_dpp v220, v220 quad_perm:[1,0,3,2] row_mask:0xf bank_mask:0xf bound_ctrl:1
	v_mov_b32_dpp v221, v221 quad_perm:[1,0,3,2] row_mask:0xf bank_mask:0xf bound_ctrl:1
	v_mov_b32_dpp v222, v222 quad_perm:[1,0,3,2] row_mask:0xf bank_mask:0xf bound_ctrl:1
	v_mov_b32_dpp v223, v223 quad_perm:[1,0,3,2] row_mask:0xf bank_mask:0xf bound_ctrl:1
	v_mov_b32_dpp v224, v224 quad_perm:[1,0,3,2] row_mask:0xf bank_mask:0xf bound_ctrl:1
	v_mov_b32_dpp v225, v225 quad_perm:[1,0,3,2] row_mask:0xf bank_mask:0xf bound_ctrl:1
	v_mov_b32_dpp v226, v226 quad_perm:[1,0,3,2] row_mask:0xf bank_mask:0xf bound_ctrl:1
	v_mov_b32_dpp v227, v227 quad_perm:[1,0,3,2] row_mask:0xf bank_mask:0xf bound_ctrl:1
	v_cndmask_b32_e64 v204, v220, v204, s[40:41]
	v_cndmask_b32_e64 v205, v205, v220, s[40:41]
	v_cndmask_b32_e64 v206, v221, v206, s[40:41]
	v_cndmask_b32_e64 v207, v207, v221, s[40:41]
	v_cndmask_b32_e64 v208, v222, v208, s[40:41]
	v_cndmask_b32_e64 v209, v209, v222, s[40:41]
	v_cndmask_b32_e64 v210, v223, v210, s[40:41]
	v_cndmask_b32_e64 v211, v211, v223, s[40:41]
	v_cndmask_b32_e64 v212, v224, v212, s[40:41]
	v_cndmask_b32_e64 v213, v213, v224, s[40:41]
	v_cndmask_b32_e64 v214, v225, v214, s[40:41]
	v_cndmask_b32_e64 v215, v215, v225, s[40:41]
	v_cndmask_b32_e64 v216, v226, v216, s[40:41]
	v_cndmask_b32_e64 v217, v217, v226, s[40:41]
	v_cndmask_b32_e64 v218, v227, v218, s[40:41]
	v_cndmask_b32_e64 v219, v219, v227, s[40:41]
	v_cvt_pk_bf16_f32 v204, v204, v205
	v_cvt_pk_bf16_f32 v206, v206, v207
	v_cvt_pk_bf16_f32 v208, v208, v209
	v_cvt_pk_bf16_f32 v210, v210, v211
	v_cvt_pk_bf16_f32 v212, v212, v213
	v_cvt_pk_bf16_f32 v214, v214, v215
	v_cvt_pk_bf16_f32 v216, v216, v217
	v_cvt_pk_bf16_f32 v218, v218, v219
	global_store_dword v236, v204, s[54:55]
	global_store_dword v236, v206, s[54:55] offset:64
	global_store_dword v237, v208, s[54:55]
	global_store_dword v237, v210, s[54:55] offset:64
	global_store_dword v238, v212, s[54:55]
	global_store_dword v238, v214, s[54:55] offset:64
	global_store_dword v239, v216, s[54:55]
	global_store_dword v239, v218, s[54:55] offset:64
